# baseline (speedup 1.0000x reference)
; #define PG8_STAGE(bufoff, gbase, voff) do { _Pragma("unroll") for (int _i = 0; _i < 2; ++_i) \
;         __builtin_amdgcn_global_load_lds((const unsigned*)((const char*)(gbase) + (voff)[_i]), (LAS unsigned*)(lds + (bufoff) + ldsw + _i * 8192), 16, 0, 0); } while (0)
; #define PG8_LDA(dst, b, h) do { _Pragma("unroll") for (int m = 0; m < 4; ++m) _Pragma("unroll") for (int k = 0; k < 2; ++k) dst[m][k] = *(const LAS bf16x8*)(lds + PG8_SA(b, h) + aoff + m * 2048 + k * 1024); } while (0)
; #define PG8_LDB(dst, b, h) do { _Pragma("unroll") for (int n = 0; n < 2; ++n) _Pragma("unroll") for (int k = 0; k < 2; ++k) dst[n][k] = *(const LAS bf16x8*)(lds + PG8_SB(b, h) + boff + n * 2048 + k * 1024); } while (0)
; #define PG8_WAIT_V(n) asm volatile("s_waitcnt vmcnt(" #n ")" ::: "memory")
; #define PG8_BAR __builtin_amdgcn_s_barrier()
;     __host__ __device__ bool next(int i, Unit& u) const {
;         const long L = (long)i * G + c; if (L >= nwg) return false;
;         int wgid = (int)L; { const int q = nwg / NXCD, r = nwg % NXCD, xcd = wgid % NXCD, off = wgid / NXCD; wgid = (xcd < r ? xcd * (q + 1) : r * (q + 1) + (xcd - r) * q) + off; }
;         const int nig = WGM * nN, gid = wgid / nig, fm = gid * WGM, gsz = (nM - fm) < WGM ? (nM - fm) : WGM;
;         u.pm = fm + ((wgid % nig) % gsz); u.pn = (wgid % nig) / gsz; return true;
;     }
; template <class Epi, class Sched>
; __device__ __forceinline__ void gemm_phase(const int tid, LAS unsigned char* lds, const Gemm g, const Sched& S, const Epi& E) {
;     ...
;         const bool has_next = S.next(ui + 1, nxt);
;         const char* nA = has_next ? (const char*)g.A + (size_t)nxt.pm * tstep : cA; const char* nB = has_next ? (const char*)g.Bt + (size_t)nxt.pn * tstep : cB;
;         for (int t = 0; t < nt; t += 2) {
;             const bool last = (t == nt - 2);
;             const char* a1 = cA + (size_t)(t + 1) * kstep;
;             const char* a2 = last ? nA : cA + (size_t)(t + 2) * kstep; const char* b2 = last ? nB : cB + (size_t)(t + 2) * kstep;
;             const char* a3 = a2 + kstep; const char* b3 = b2 + kstep;
;             if (last && has_next) S.a_ready(nxt);
;             PG8_LDB(B0, 0, 0); PG8_LDB(B1, 0, 1); PG8_SCHED; PG8_LDA(At, 0, 0); PG8_STAGE(PG8_SA(1, 1), a1 + hstep, voffA);
;             PG8_WAIT_V(8); PG8_WAIT_L(0); PG8_BAR; PG8_MMA(0, 0, At, B0); PG8_MMA(0, 1, At, B1); PG8_BAR; PG8_SCHED;
.LBB0_667:
	s_mov_b64 s[86:87], s[22:23]
	s_mov_b64 s[88:89], s[24:25]
	s_add_u32 s22, s22, 0x80080
	s_addc_u32 s23, s23, 0
	s_add_u32 s70, s24, 0x100
	v_mov_b32_e32 v0, 0
	s_addc_u32 s71, s25, 0
	s_mov_b32 s72, -2
	s_add_u32 s24, s22, 0xfff80080
	s_addc_u32 s25, s23, -1
	s_add_i32 s73, 0, 0x10000
	s_cmp_eq_u32 s72, 28
	s_cselect_b32 s27, s15, s25
	s_cselect_b32 s26, s68, s24
	s_cselect_b32 s25, s13, s71
	s_cselect_b32 s24, s69, s70
	s_add_i32 s76, 0, 0x14000
	v_add_u32_e32 v172, s73, v170
	v_add_u32_e32 v188, s76, v170
	ds_read_b128 v[138:141], v172
	ds_read_b128 v[142:145], v172 offset:1024
	ds_read_b128 v[146:149], v172 offset:2048
	ds_read_b128 v[172:175], v172 offset:3072
	ds_read_b128 v[176:179], v188
	ds_read_b128 v[180:183], v188 offset:1024
	ds_read_b128 v[184:187], v188 offset:2048
	ds_read_b128 v[188:191], v188 offset:3072
	v_lshl_add_u64 v[232:233], s[22:23], 0, v[134:135]
	s_add_i32 m0, s58, 0xc000
	ds_read_b128 v[200:203], v171
	ds_read_b128 v[204:207], v171 offset:1024
	ds_read_b128 v[208:211], v171 offset:2048
	ds_read_b128 v[212:215], v171 offset:3072
	ds_read_b128 v[216:219], v171 offset:4096
	ds_read_b128 v[220:223], v171 offset:5120
	ds_read_b128 v[224:227], v171 offset:6144
	ds_read_b128 v[228:231], v171 offset:7168
	global_load_lds_dwordx4 v[232:233], off
	v_lshl_add_u64 v[232:233], s[22:23], 0, v[136:137]
	s_add_i32 m0, s58, 0xe000
	s_nop 0
	global_load_lds_dwordx4 v[232:233], off
	s_add_i32 s67, s67, 1
	s_mul_i32 s0, s67, s30
	s_mul_hi_u32 s1, s67, s29
	s_add_i32 s1, s1, s0
	s_mul_i32 s0, s67, s29
	s_add_u32 s16, s0, s4
	s_addc_u32 s17, s1, s5
	v_cmp_gt_i64_e32 vcc, s[16:17], v[168:169]
	v_cmp_lt_i64_e64 s[0:1], s[16:17], v[166:167]
	s_cbranch_vccnz .LBB0_669
	s_ashr_i32 s12, s16, 31
	s_lshr_b32 s12, s12, 29
	s_add_i32 s12, s16, s12
	s_ashr_i32 s13, s12, 3
	s_and_b32 s12, s12, -8
	s_sub_i32 s12, s16, s12
	s_cmp_lt_i32 s12, 0
	s_movk_i32 s14, 0x2c1
	s_cselect_b32 s14, s14, 0x2c0
	s_mul_i32 s12, s12, s14
	s_add_i32 s12, s12, s13
	s_mul_hi_i32 s13, s12, 0x2e8ba2e9
	s_lshr_b32 s14, s13, 31
	s_ashr_i32 s13, s13, 5
	s_add_i32 s13, s13, s14
	s_lshl_b32 s14, s13, 2
	s_sub_i32 s15, 0x80, s14
	s_min_i32 s15, s15, 4
	s_abs_i32 s16, s15
	v_cvt_f32_u32_e32 v244, s16
	s_sub_i32 s18, 0, s16
	s_mulk_i32 s13, 0xb0
	s_sub_i32 s13, s12, s13
	v_rcp_iflag_f32_e32 v244, v244
	s_abs_i32 s12, s13
	s_xor_b32 s17, s13, s15
	s_ashr_i32 s17, s17, 31
	v_mul_f32_e32 v244, 0x4f7ffffe, v244
	v_cvt_u32_f32_e32 v244, v244
	s_nop 0
	v_readfirstlane_b32 s19, v244
	s_mul_i32 s18, s18, s19
	s_mul_hi_u32 s18, s19, s18
	s_add_i32 s19, s19, s18
	s_mul_hi_u32 s18, s12, s19
	s_mul_i32 s19, s18, s16
	s_sub_i32 s12, s12, s19
	s_add_i32 s90, s18, 1
	s_sub_i32 s19, s12, s16
	s_cmp_ge_u32 s12, s16
	s_cselect_b32 s18, s90, s18
	s_cselect_b32 s12, s19, s12
	s_add_i32 s19, s18, 1
	s_cmp_ge_u32 s12, s16
	s_cselect_b32 s12, s19, s18
	s_xor_b32 s12, s12, s17
	s_sub_i32 s12, s12, s17
	s_mul_i32 s15, s12, s15
	s_sub_i32 s13, s13, s15
	s_add_i32 s14, s14, s13
.LBB0_669:
	s_ashr_i32 s15, s14, 31
	s_lshl_b64 s[16:17], s[14:15], 20
	s_add_u32 s16, s56, s16
	s_addc_u32 s17, s57, s17
	s_and_b64 s[18:19], s[0:1], exec
	s_cselect_b32 s15, s17, s87
	s_cselect_b32 s68, s16, s86
	s_ashr_i32 s13, s12, 31
	s_lshl_b64 s[18:19], s[12:13], 20
	s_add_u32 s18, s41, s18
	s_addc_u32 s19, s55, s19
	s_and_b64 s[90:91], s[0:1], exec
	s_cselect_b32 s13, s19, s89
	s_cselect_b32 s69, s18, s88
	s_waitcnt vmcnt(8)
	s_waitcnt lgkmcnt(0)
	s_barrier
	s_setprio 1
	s_waitcnt lgkmcnt(0)
	v_mfma_f32_16x16x32_bf16 v[124:127], v[138:141], v[200:203], 0
	v_mfma_f32_16x16x32_bf16 v[116:119], v[146:149], v[200:203], 0
	v_mfma_f32_16x16x32_bf16 v[108:111], v[138:141], v[208:211], 0
	v_mfma_f32_16x16x32_bf16 v[100:103], v[146:149], v[208:211], 0
	v_mfma_f32_16x16x32_bf16 v[92:95], v[138:141], v[216:219], 0
	v_mfma_f32_16x16x32_bf16 v[84:87], v[146:149], v[216:219], 0
	v_mfma_f32_16x16x32_bf16 v[76:79], v[138:141], v[224:227], 0
	v_mfma_f32_16x16x32_bf16 v[68:71], v[146:149], v[224:227], 0
	v_mfma_f32_16x16x32_bf16 v[124:127], v[142:145], v[204:207], v[124:127]
	v_mfma_f32_16x16x32_bf16 v[116:119], v[172:175], v[204:207], v[116:119]
	v_mfma_f32_16x16x32_bf16 v[108:111], v[142:145], v[212:215], v[108:111]
	v_mfma_f32_16x16x32_bf16 v[100:103], v[172:175], v[212:215], v[100:103]
	v_mfma_f32_16x16x32_bf16 v[92:95], v[142:145], v[220:223], v[92:95]
	v_mfma_f32_16x16x32_bf16 v[84:87], v[172:175], v[220:223], v[84:87]
	v_mfma_f32_16x16x32_bf16 v[76:79], v[142:145], v[228:231], v[76:79]
	v_mfma_f32_16x16x32_bf16 v[68:71], v[172:175], v[228:231], v[68:71]
	s_setprio 0
	s_setprio 1
	v_mfma_f32_16x16x32_bf16 v[120:123], v[176:179], v[200:203], 0
	v_mfma_f32_16x16x32_bf16 v[112:115], v[184:187], v[200:203], 0
	v_mfma_f32_16x16x32_bf16 v[104:107], v[176:179], v[208:211], 0
	v_mfma_f32_16x16x32_bf16 v[96:99], v[184:187], v[208:211], 0
	v_mfma_f32_16x16x32_bf16 v[88:91], v[176:179], v[216:219], 0
	v_mfma_f32_16x16x32_bf16 v[80:83], v[184:187], v[216:219], 0
	v_mfma_f32_16x16x32_bf16 v[72:75], v[176:179], v[224:227], 0
	v_mfma_f32_16x16x32_bf16 v[64:67], v[184:187], v[224:227], 0
	v_mfma_f32_16x16x32_bf16 v[120:123], v[180:183], v[204:207], v[120:123]
	v_mfma_f32_16x16x32_bf16 v[112:115], v[188:191], v[204:207], v[112:115]
	v_mfma_f32_16x16x32_bf16 v[104:107], v[180:183], v[212:215], v[104:107]
	v_mfma_f32_16x16x32_bf16 v[96:99], v[188:191], v[212:215], v[96:99]
	v_mfma_f32_16x16x32_bf16 v[88:91], v[180:183], v[220:223], v[88:91]
	v_mfma_f32_16x16x32_bf16 v[80:83], v[188:191], v[220:223], v[80:83]
	v_mfma_f32_16x16x32_bf16 v[72:75], v[180:183], v[228:231], v[72:75]
	v_mfma_f32_16x16x32_bf16 v[64:67], v[188:191], v[228:231], v[64:67]
	s_setprio 0
	s_barrier
; #define PG8_STAGE(bufoff, gbase, voff) do { _Pragma("unroll") for (int _i = 0; _i < 2; ++_i) \
;         __builtin_amdgcn_global_load_lds((const unsigned*)((const char*)(gbase) + (voff)[_i]), (LAS unsigned*)(lds + (bufoff) + ldsw + _i * 8192), 16, 0, 0); } while (0)
; #define PG8_LDA(dst, b, h) do { _Pragma("unroll") for (int m = 0; m < 4; ++m) _Pragma("unroll") for (int k = 0; k < 2; ++k) dst[m][k] = *(const LAS bf16x8*)(lds + PG8_SA(b, h) + aoff + m * 2048 + k * 1024); } while (0)
; #define PG8_LDB(dst, b, h) do { _Pragma("unroll") for (int n = 0; n < 2; ++n) _Pragma("unroll") for (int k = 0; k < 2; ++k) dst[n][k] = *(const LAS bf16x8*)(lds + PG8_SB(b, h) + boff + n * 2048 + k * 1024); } while (0)
; #define PG8_MMA(ai, bj, At, Bt) do { __builtin_amdgcn_s_setprio(1); _Pragma("unroll") for (int m = 0; m < 4; ++m) _Pragma("unroll") for (int n = 0; n < 2; ++n) _Pragma("unroll") for (int k = 0; k < 2; ++k) \
;         acc[ai][bj][m][n] = __builtin_amdgcn_mfma_f32_16x16x32_bf16(Bt[n][k], At[m][k], acc[ai][bj][m][n], 0, 0, 0); __builtin_amdgcn_s_setprio(0); } while (0)
; #define PG8_WAIT_V(n) asm volatile("s_waitcnt vmcnt(" #n ")" ::: "memory")
; #define PG8_WAIT_L(n) asm volatile("s_waitcnt lgkmcnt(" #n ")" ::: "memory")
; #define PG8_BAR __builtin_amdgcn_s_barrier()
; #define PG8_SCHED __builtin_amdgcn_sched_barrier(0)
; template <class Epi, class Sched>
; __device__ __forceinline__ void gemm_phase(const int tid, LAS unsigned char* lds, const Gemm g, const Sched& S, const Epi& E) {
;     ...
;             PG8_WAIT_V(8); PG8_WAIT_L(0); PG8_BAR; PG8_MMA(0, 0, At, B0); PG8_MMA(0, 1, At, B1); PG8_BAR; PG8_SCHED;
;             PG8_LDA(At, 0, 1); PG8_STAGE(PG8_SB(0, 0), b2, voffB); PG8_STAGE(PG8_SB(0, 1), b2 + hstep, voffB); PG8_STAGE(PG8_SA(0, 0), a2, voffA);
;             PG8_WAIT_V(8); PG8_WAIT_L(0); PG8_BAR; PG8_MMA(1, 0, At, B0); PG8_MMA(1, 1, At, B1); PG8_BAR; PG8_SCHED;
;             PG8_LDB(B0, 1, 0); PG8_LDB(B1, 1, 1); PG8_SCHED; PG8_LDA(At, 1, 0); PG8_STAGE(PG8_SA(0, 1), a2 + hstep, voffA);
;             PG8_WAIT_V(8); PG8_WAIT_L(0); PG8_BAR; PG8_MMA(0, 0, At, B0); PG8_MMA(0, 1, At, B1); PG8_BAR; PG8_SCHED;
	s_add_i32 s73, s73, s40
	v_lshl_add_u64 v[232:233], s[24:25], 0, v[152:153]
	s_mov_b32 m0, s73
	ds_read_b128 v[200:203], v171 offset:16384
	ds_read_b128 v[204:207], v171 offset:17408
	ds_read_b128 v[208:211], v171 offset:18432
	ds_read_b128 v[212:215], v171 offset:19456
	ds_read_b128 v[216:219], v171 offset:20480
	ds_read_b128 v[220:223], v171 offset:21504
	ds_read_b128 v[224:227], v171 offset:22528
	ds_read_b128 v[228:231], v171 offset:23552
	global_load_lds_dwordx4 v[232:233], off
	s_add_i32 m0, s73, 0x2000
	s_add_u32 s74, s24, 0x80000
	v_lshl_add_u64 v[234:235], s[24:25], 0, v[128:129]
	s_addc_u32 s75, s25, 0
	s_add_i32 s73, s76, s40
	global_load_lds_dwordx4 v[234:235], off
	v_lshl_add_u64 v[236:237], s[74:75], 0, v[152:153]
	s_mov_b32 m0, s73
	v_lshl_add_u64 v[238:239], s[26:27], 0, v[130:131]
	global_load_lds_dwordx4 v[236:237], off
	v_lshl_add_u64 v[236:237], s[74:75], 0, v[128:129]
	s_add_i32 m0, s73, 0x2000
	s_nop 0
	global_load_lds_dwordx4 v[236:237], off
	v_lshl_add_u64 v[236:237], s[26:27], 0, v[132:133]
	s_mov_b32 m0, s58
	s_nop 0
	global_load_lds_dwordx4 v[236:237], off
	s_mov_b32 m0, s59
	s_nop 0
	global_load_lds_dwordx4 v[238:239], off
	s_waitcnt vmcnt(8)
	s_waitcnt lgkmcnt(0)
	s_barrier
	s_setprio 1
	s_waitcnt lgkmcnt(0)
	v_mfma_f32_16x16x32_bf16 v[60:63], v[138:141], v[200:203], 0
	v_mfma_f32_16x16x32_bf16 v[52:55], v[146:149], v[200:203], 0
	v_mfma_f32_16x16x32_bf16 v[44:47], v[138:141], v[208:211], 0
	v_mfma_f32_16x16x32_bf16 v[36:39], v[146:149], v[208:211], 0
	v_mfma_f32_16x16x32_bf16 v[28:31], v[138:141], v[216:219], 0
	v_mfma_f32_16x16x32_bf16 v[20:23], v[146:149], v[216:219], 0
	v_mfma_f32_16x16x32_bf16 v[12:15], v[138:141], v[224:227], 0
	v_mfma_f32_16x16x32_bf16 v[4:7], v[146:149], v[224:227], 0
	v_mfma_f32_16x16x32_bf16 v[60:63], v[142:145], v[204:207], v[60:63]
	v_mfma_f32_16x16x32_bf16 v[52:55], v[172:175], v[204:207], v[52:55]
	v_mfma_f32_16x16x32_bf16 v[44:47], v[142:145], v[212:215], v[44:47]
	v_mfma_f32_16x16x32_bf16 v[36:39], v[172:175], v[212:215], v[36:39]
	v_mfma_f32_16x16x32_bf16 v[28:31], v[142:145], v[220:223], v[28:31]
	v_mfma_f32_16x16x32_bf16 v[20:23], v[172:175], v[220:223], v[20:23]
	v_mfma_f32_16x16x32_bf16 v[12:15], v[142:145], v[228:231], v[12:15]
	v_mfma_f32_16x16x32_bf16 v[4:7], v[172:175], v[228:231], v[4:7]
	s_setprio 0
	s_setprio 1
	v_mfma_f32_16x16x32_bf16 v[56:59], v[176:179], v[200:203], 0
	v_mfma_f32_16x16x32_bf16 v[48:51], v[184:187], v[200:203], 0
	v_mfma_f32_16x16x32_bf16 v[40:43], v[176:179], v[208:211], 0
	v_mfma_f32_16x16x32_bf16 v[32:35], v[184:187], v[208:211], 0
	v_mfma_f32_16x16x32_bf16 v[24:27], v[176:179], v[216:219], 0
	v_mfma_f32_16x16x32_bf16 v[16:19], v[184:187], v[216:219], 0
	v_mfma_f32_16x16x32_bf16 v[8:11], v[176:179], v[224:227], 0
	v_mfma_f32_16x16x32_bf16 v[0:3], v[184:187], v[224:227], 0
	v_mfma_f32_16x16x32_bf16 v[56:59], v[180:183], v[204:207], v[56:59]
	v_mfma_f32_16x16x32_bf16 v[48:51], v[188:191], v[204:207], v[48:51]
	v_mfma_f32_16x16x32_bf16 v[40:43], v[180:183], v[212:215], v[40:43]
	v_mfma_f32_16x16x32_bf16 v[32:35], v[188:191], v[212:215], v[32:35]
	v_mfma_f32_16x16x32_bf16 v[24:27], v[180:183], v[220:223], v[24:27]
	v_mfma_f32_16x16x32_bf16 v[16:19], v[188:191], v[220:223], v[16:19]
	v_mfma_f32_16x16x32_bf16 v[8:11], v[180:183], v[228:231], v[8:11]
	v_mfma_f32_16x16x32_bf16 v[0:3], v[188:191], v[228:231], v[0:3]
	s_setprio 0
	s_barrier
	s_add_i32 s73, 0, 0x18000
	s_add_i32 s74, 0, 0x1c000
	v_add_u32_e32 v172, s73, v170
	v_add_u32_e32 v188, s74, v170
	ds_read_b128 v[138:141], v172
	ds_read_b128 v[142:145], v172 offset:1024
	ds_read_b128 v[146:149], v172 offset:2048
	ds_read_b128 v[172:175], v172 offset:3072
	ds_read_b128 v[176:179], v188
	ds_read_b128 v[180:183], v188 offset:1024
	ds_read_b128 v[184:187], v188 offset:2048
	ds_read_b128 v[188:191], v188 offset:3072
	s_add_u32 s26, s26, 0x80000
	s_addc_u32 s27, s27, 0
	s_mov_b32 m0, s60
	v_lshl_add_u64 v[240:241], s[26:27], 0, v[132:133]
	ds_read_b128 v[200:203], v171 offset:32768
	ds_read_b128 v[204:207], v171 offset:33792
	ds_read_b128 v[208:211], v171 offset:34816
	ds_read_b128 v[212:215], v171 offset:35840
	ds_read_b128 v[216:219], v171 offset:36864
	ds_read_b128 v[220:223], v171 offset:37888
	ds_read_b128 v[224:227], v171 offset:38912
	ds_read_b128 v[228:231], v171 offset:39936
	global_load_lds_dwordx4 v[240:241], off
	v_lshl_add_u64 v[240:241], s[26:27], 0, v[130:131]
	s_mov_b32 m0, s61
	s_nop 0
	global_load_lds_dwordx4 v[240:241], off
	s_waitcnt vmcnt(8)
	s_waitcnt lgkmcnt(0)
	s_barrier
; #define PG8_STAGE(bufoff, gbase, voff) do { _Pragma("unroll") for (int _i = 0; _i < 2; ++_i) \
;         __builtin_amdgcn_global_load_lds((const unsigned*)((const char*)(gbase) + (voff)[_i]), (LAS unsigned*)(lds + (bufoff) + ldsw + _i * 8192), 16, 0, 0); } while (0)
; #define PG8_LDA(dst, b, h) do { _Pragma("unroll") for (int m = 0; m < 4; ++m) _Pragma("unroll") for (int k = 0; k < 2; ++k) dst[m][k] = *(const LAS bf16x8*)(lds + PG8_SA(b, h) + aoff + m * 2048 + k * 1024); } while (0)
; #define PG8_MMA(ai, bj, At, Bt) do { __builtin_amdgcn_s_setprio(1); _Pragma("unroll") for (int m = 0; m < 4; ++m) _Pragma("unroll") for (int n = 0; n < 2; ++n) _Pragma("unroll") for (int k = 0; k < 2; ++k) \
;         acc[ai][bj][m][n] = __builtin_amdgcn_mfma_f32_16x16x32_bf16(Bt[n][k], At[m][k], acc[ai][bj][m][n], 0, 0, 0); __builtin_amdgcn_s_setprio(0); } while (0)
; #define PG8_WAIT_V(n) asm volatile("s_waitcnt vmcnt(" #n ")" ::: "memory")
; #define PG8_WAIT_L(n) asm volatile("s_waitcnt lgkmcnt(" #n ")" ::: "memory")
; #define PG8_BAR __builtin_amdgcn_s_barrier()
; #define PG8_SCHED __builtin_amdgcn_sched_barrier(0)
; template <class Epi, class Sched>
; __device__ __forceinline__ void gemm_phase(const int tid, LAS unsigned char* lds, const Gemm g, const Sched& S, const Epi& E) {
;     ...
;             PG8_WAIT_V(8); PG8_WAIT_L(0); PG8_BAR; PG8_MMA(0, 0, At, B0); PG8_MMA(0, 1, At, B1); PG8_BAR; PG8_SCHED;
;             PG8_LDA(At, 1, 1); PG8_STAGE(PG8_SB(1, 0), b3, voffB); PG8_STAGE(PG8_SB(1, 1), b3 + hstep, voffB); PG8_STAGE(PG8_SA(1, 0), a3, voffA);
;             PG8_WAIT_V(8); PG8_WAIT_L(0); PG8_BAR; PG8_MMA(1, 0, At, B0); PG8_MMA(1, 1, At, B1); PG8_BAR; PG8_SCHED;
;         }
	s_setprio 1
	s_waitcnt lgkmcnt(0)
	v_mfma_f32_16x16x32_bf16 v[124:127], v[138:141], v[200:203], v[124:127]
	v_mfma_f32_16x16x32_bf16 v[116:119], v[146:149], v[200:203], v[116:119]
	v_mfma_f32_16x16x32_bf16 v[108:111], v[138:141], v[208:211], v[108:111]
	v_mfma_f32_16x16x32_bf16 v[100:103], v[146:149], v[208:211], v[100:103]
	v_mfma_f32_16x16x32_bf16 v[92:95], v[138:141], v[216:219], v[92:95]
	v_mfma_f32_16x16x32_bf16 v[84:87], v[146:149], v[216:219], v[84:87]
	v_mfma_f32_16x16x32_bf16 v[76:79], v[138:141], v[224:227], v[76:79]
	v_mfma_f32_16x16x32_bf16 v[68:71], v[146:149], v[224:227], v[68:71]
	v_mfma_f32_16x16x32_bf16 v[124:127], v[142:145], v[204:207], v[124:127]
	v_mfma_f32_16x16x32_bf16 v[116:119], v[172:175], v[204:207], v[116:119]
	v_mfma_f32_16x16x32_bf16 v[108:111], v[142:145], v[212:215], v[108:111]
	v_mfma_f32_16x16x32_bf16 v[100:103], v[172:175], v[212:215], v[100:103]
	v_mfma_f32_16x16x32_bf16 v[92:95], v[142:145], v[220:223], v[92:95]
	v_mfma_f32_16x16x32_bf16 v[84:87], v[172:175], v[220:223], v[84:87]
	v_mfma_f32_16x16x32_bf16 v[76:79], v[142:145], v[228:231], v[76:79]
	v_mfma_f32_16x16x32_bf16 v[68:71], v[172:175], v[228:231], v[68:71]
	s_setprio 0
	s_setprio 1
	v_mfma_f32_16x16x32_bf16 v[120:123], v[176:179], v[200:203], v[120:123]
	v_mfma_f32_16x16x32_bf16 v[112:115], v[184:187], v[200:203], v[112:115]
	v_mfma_f32_16x16x32_bf16 v[104:107], v[176:179], v[208:211], v[104:107]
	v_mfma_f32_16x16x32_bf16 v[96:99], v[184:187], v[208:211], v[96:99]
	v_mfma_f32_16x16x32_bf16 v[88:91], v[176:179], v[216:219], v[88:91]
	v_mfma_f32_16x16x32_bf16 v[80:83], v[184:187], v[216:219], v[80:83]
	v_mfma_f32_16x16x32_bf16 v[72:75], v[176:179], v[224:227], v[72:75]
	v_mfma_f32_16x16x32_bf16 v[64:67], v[184:187], v[224:227], v[64:67]
	v_mfma_f32_16x16x32_bf16 v[120:123], v[180:183], v[204:207], v[120:123]
	v_mfma_f32_16x16x32_bf16 v[112:115], v[188:191], v[204:207], v[112:115]
	v_mfma_f32_16x16x32_bf16 v[104:107], v[180:183], v[212:215], v[104:107]
	v_mfma_f32_16x16x32_bf16 v[96:99], v[188:191], v[212:215], v[96:99]
	v_mfma_f32_16x16x32_bf16 v[88:91], v[180:183], v[220:223], v[88:91]
	v_mfma_f32_16x16x32_bf16 v[80:83], v[188:191], v[220:223], v[80:83]
	v_mfma_f32_16x16x32_bf16 v[72:75], v[180:183], v[228:231], v[72:75]
	v_mfma_f32_16x16x32_bf16 v[64:67], v[188:191], v[228:231], v[64:67]
	s_setprio 0
	s_barrier
	s_add_i32 s26, s73, s40
	v_lshl_add_u64 v[232:233], v[232:233], 0, s[34:35]
	s_mov_b32 m0, s26
	ds_read_b128 v[200:203], v171 offset:49152
	ds_read_b128 v[204:207], v171 offset:50176
	ds_read_b128 v[208:211], v171 offset:51200
	ds_read_b128 v[212:215], v171 offset:52224
	ds_read_b128 v[216:219], v171 offset:53248
	ds_read_b128 v[220:223], v171 offset:54272
	ds_read_b128 v[224:227], v171 offset:55296
	ds_read_b128 v[228:231], v171 offset:56320
	global_load_lds_dwordx4 v[232:233], off
	s_add_i32 m0, s26, 0x2000
	s_add_u32 s24, s24, 0x80080
	v_lshl_add_u64 v[232:233], v[234:235], 0, s[34:35]
	s_addc_u32 s25, s25, 0
	s_add_i32 s26, s74, s40
	global_load_lds_dwordx4 v[232:233], off
	v_lshl_add_u64 v[232:233], s[24:25], 0, v[152:153]
	s_mov_b32 m0, s26
	s_nop 0
	global_load_lds_dwordx4 v[232:233], off
	v_lshl_add_u64 v[232:233], s[24:25], 0, v[128:129]
	s_add_i32 m0, s26, 0x2000
	s_nop 0
	global_load_lds_dwordx4 v[232:233], off
	v_lshl_add_u64 v[232:233], v[236:237], 0, s[34:35]
	s_mov_b32 m0, s64
	s_nop 0
	global_load_lds_dwordx4 v[232:233], off
	v_lshl_add_u64 v[232:233], v[238:239], 0, s[34:35]
	s_mov_b32 m0, s65
	s_nop 0
	global_load_lds_dwordx4 v[232:233], off
	s_waitcnt vmcnt(8)
	s_waitcnt lgkmcnt(0)
	s_barrier
	s_setprio 1
	s_waitcnt lgkmcnt(0)
	v_mfma_f32_16x16x32_bf16 v[60:63], v[138:141], v[200:203], v[60:63]
	v_mfma_f32_16x16x32_bf16 v[52:55], v[146:149], v[200:203], v[52:55]
	v_mfma_f32_16x16x32_bf16 v[44:47], v[138:141], v[208:211], v[44:47]
	v_mfma_f32_16x16x32_bf16 v[36:39], v[146:149], v[208:211], v[36:39]
	v_mfma_f32_16x16x32_bf16 v[28:31], v[138:141], v[216:219], v[28:31]
	v_mfma_f32_16x16x32_bf16 v[20:23], v[146:149], v[216:219], v[20:23]
	v_mfma_f32_16x16x32_bf16 v[12:15], v[138:141], v[224:227], v[12:15]
	v_mfma_f32_16x16x32_bf16 v[4:7], v[146:149], v[224:227], v[4:7]
	v_mfma_f32_16x16x32_bf16 v[60:63], v[142:145], v[204:207], v[60:63]
	v_mfma_f32_16x16x32_bf16 v[52:55], v[172:175], v[204:207], v[52:55]
	v_mfma_f32_16x16x32_bf16 v[44:47], v[142:145], v[212:215], v[44:47]
	v_mfma_f32_16x16x32_bf16 v[36:39], v[172:175], v[212:215], v[36:39]
	v_mfma_f32_16x16x32_bf16 v[28:31], v[142:145], v[220:223], v[28:31]
	v_mfma_f32_16x16x32_bf16 v[20:23], v[172:175], v[220:223], v[20:23]
	v_mfma_f32_16x16x32_bf16 v[12:15], v[142:145], v[228:231], v[12:15]
	v_mfma_f32_16x16x32_bf16 v[4:7], v[172:175], v[228:231], v[4:7]
	s_setprio 0
	s_setprio 1
	v_mfma_f32_16x16x32_bf16 v[56:59], v[176:179], v[200:203], v[56:59]
	v_mfma_f32_16x16x32_bf16 v[48:51], v[184:187], v[200:203], v[48:51]
	v_mfma_f32_16x16x32_bf16 v[40:43], v[176:179], v[208:211], v[40:43]
	v_mfma_f32_16x16x32_bf16 v[32:35], v[184:187], v[208:211], v[32:35]
	v_mfma_f32_16x16x32_bf16 v[24:27], v[176:179], v[216:219], v[24:27]
	v_mfma_f32_16x16x32_bf16 v[16:19], v[184:187], v[216:219], v[16:19]
	v_mfma_f32_16x16x32_bf16 v[8:11], v[176:179], v[224:227], v[8:11]
	v_mfma_f32_16x16x32_bf16 v[0:3], v[184:187], v[224:227], v[0:3]
	v_mfma_f32_16x16x32_bf16 v[56:59], v[180:183], v[204:207], v[56:59]
	v_mfma_f32_16x16x32_bf16 v[48:51], v[188:191], v[204:207], v[48:51]
	v_mfma_f32_16x16x32_bf16 v[40:43], v[180:183], v[212:215], v[40:43]
	v_mfma_f32_16x16x32_bf16 v[32:35], v[188:191], v[212:215], v[32:35]
	v_mfma_f32_16x16x32_bf16 v[24:27], v[180:183], v[220:223], v[24:27]
	v_mfma_f32_16x16x32_bf16 v[16:19], v[188:191], v[220:223], v[16:19]
	v_mfma_f32_16x16x32_bf16 v[8:11], v[180:183], v[228:231], v[8:11]
	v_mfma_f32_16x16x32_bf16 v[0:3], v[188:191], v[228:231], v[0:3]
	s_setprio 0
	s_barrier
	s_add_i32 s72, s72, 2
	s_add_u32 s22, s22, 0x100
	s_addc_u32 s23, s23, 0
	s_add_u32 s70, s70, 0x100
	s_addc_u32 s71, s71, 0
	s_cmp_gt_u32 s72, 29
